# gMLP and pooling items: the 12 loads of each unrolled epilogue-loop body issued together at the body top (were 4 serialized load->wait->store steps per body); broadcast pk_add split into scalar adds
# baseline (speedup 1.0000x reference)
.LBB0_670:
	v_add_u32_e32 v14, s20, v20
	v_mov_b64_e32 v[16:17], s[6:7]
	v_mad_i64_i32 v[0:1], s[22:23], v14, s0, v[16:17]
	s_lshl_b32 s70, s43, 1
	v_lshl_add_u64 v[0:1], v[0:1], 0, s[70:71]
	v_lshl_add_u64 v[0:1], v[0:1], 0, v[160:161]
	v_add_co_u32_e32 v0, vcc, 0x1000, v0
	v_ashrrev_i32_e32 v15, 31, v14
	s_nop 0
	v_addc_co_u32_e32 v1, vcc, 0, v1, vcc
	global_load_dwordx4 v[0:3], v[0:1], off
	s_nop 0
	global_load_dwordx4 v[4:7], v[12:13], off offset:16
	global_load_dwordx4 v[8:11], v[12:13], off
	ds_read_b128 v[22:25], v21
	ds_read_b128 v[26:29], v21 offset:16
	s_add_i32 s20, s20, 16
	s_cmp_lg_u32 s20, 32
	s_waitcnt vmcnt(3)
	v_add_u32_e32 v64, 4, v14
	v_mad_i64_i32 v[68:69], s[100:101], v64, s0, v[16:17]
	v_lshl_add_u64 v[70:71], v[68:69], 0, s[70:71]
	v_lshl_add_u64 v[72:73], v[70:71], 0, v[160:161]
	v_add_co_u32_e32 v72, vcc, s21, v72
	s_nop 1
	v_addc_co_u32_e32 v73, vcc, 0, v73, vcc
	global_load_dwordx4 v[74:77], v[72:73], off
	global_load_dwordx4 v[78:81], v[12:13], off offset:16
	global_load_dwordx4 v[82:85], v[12:13], off
	v_add_u32_e32 v86, 8, v14
	v_mad_i64_i32 v[90:91], s[100:101], v86, s0, v[16:17]
	v_lshl_add_u64 v[92:93], v[90:91], 0, s[70:71]
	v_lshl_add_u64 v[110:111], v[92:93], 0, v[160:161]
	v_add_co_u32_e32 v110, vcc, s21, v110
	s_nop 1
	v_addc_co_u32_e32 v111, vcc, 0, v111, vcc
	global_load_dwordx4 v[112:115], v[110:111], off
	global_load_dwordx4 v[116:119], v[12:13], off offset:16
	global_load_dwordx4 v[120:123], v[12:13], off
	v_add_u32_e32 v124, 12, v14
	v_mad_i64_i32 v[128:129], s[100:101], v124, s0, v[16:17]
	v_lshl_add_u64 v[130:131], v[128:129], 0, s[70:71]
	v_lshl_add_u64 v[132:133], v[130:131], 0, v[160:161]
	v_add_co_u32_e32 v132, vcc, s21, v132
	s_nop 1
	v_addc_co_u32_e32 v133, vcc, 0, v133, vcc
	global_load_dwordx4 v[134:137], v[132:133], off
	global_load_dwordx4 v[138:141], v[12:13], off offset:16
	global_load_dwordx4 v[142:145], v[12:13], off
	s_waitcnt vmcnt(11)
	v_and_b32_e32 v30, 0xffff0000, v0
	v_lshlrev_b32_e32 v0, 16, v0
	v_mul_f32_e32 v18, 0xbfb8aa3b, v0
	v_mul_f32_e32 v19, 0xbfb8aa3b, v30
	v_exp_f32_e32 v18, v18
	v_exp_f32_e32 v19, v19
	s_waitcnt  lgkmcnt(1)
	s_waitcnt vmcnt(9)
	v_pk_mul_f32 v[8:9], v[8:9], v[22:23]
	v_pk_mul_f32 v[10:11], v[10:11], v[24:25]
	s_waitcnt lgkmcnt(0)
	v_pk_mul_f32 v[4:5], v[4:5], v[26:27]
	v_pk_add_f32 v[18:19], v[18:19], 1.0 op_sel_hi:[1,0]
	v_pk_mul_f32 v[6:7], v[6:7], v[28:29]
	v_div_scale_f32 v22, s[22:23], v19, v19, v30
	v_rcp_f32_e32 v23, v22
	s_nop 0
	v_fma_f32 v31, -v22, v23, 1.0
	v_fmac_f32_e32 v23, v31, v23
	v_div_scale_f32 v31, vcc, v30, v19, v30
	v_mul_f32_e32 v32, v31, v23
	v_fma_f32 v33, -v22, v32, v31
	v_fmac_f32_e32 v32, v33, v23
	v_fma_f32 v22, -v22, v32, v31
	v_div_fmas_f32 v22, v22, v23, v32
	v_div_fixup_f32 v19, v22, v19, v30
	v_div_scale_f32 v22, s[22:23], v18, v18, v0
	v_rcp_f32_e32 v23, v22
	s_nop 0
	v_fma_f32 v30, -v22, v23, 1.0
	v_fmac_f32_e32 v23, v30, v23
	v_div_scale_f32 v30, vcc, v0, v18, v0
	v_mul_f32_e32 v31, v30, v23
	v_fma_f32 v32, -v22, v31, v30
	v_fmac_f32_e32 v31, v32, v23
	v_fma_f32 v22, -v22, v31, v30
	v_div_fmas_f32 v22, v22, v23, v31
	v_div_fixup_f32 v18, v22, v18, v0
	v_pk_mul_f32 v[8:9], v[18:19], v[8:9]
	v_and_b32_e32 v18, 0xffff0000, v1
	v_lshlrev_b32_e32 v19, 16, v1
	v_mul_f32_e32 v0, 0xbfb8aa3b, v19
	v_mul_f32_e32 v1, 0xbfb8aa3b, v18
	v_exp_f32_e32 v0, v0
	v_exp_f32_e32 v1, v1
	s_nop 0
	v_pk_add_f32 v[0:1], v[0:1], 1.0 op_sel_hi:[1,0]
	s_nop 0
	v_div_scale_f32 v22, s[22:23], v1, v1, v18
	v_rcp_f32_e32 v23, v22
	s_nop 0
	v_fma_f32 v24, -v22, v23, 1.0
	v_fmac_f32_e32 v23, v24, v23
	v_div_scale_f32 v24, vcc, v18, v1, v18
	v_mul_f32_e32 v25, v24, v23
	v_fma_f32 v30, -v22, v25, v24
	v_fmac_f32_e32 v25, v30, v23
	v_fma_f32 v22, -v22, v25, v24
	v_div_fmas_f32 v22, v22, v23, v25
	v_div_fixup_f32 v1, v22, v1, v18
	v_div_scale_f32 v18, s[22:23], v0, v0, v19
	v_rcp_f32_e32 v22, v18
	s_nop 0
	v_fma_f32 v23, -v18, v22, 1.0
	v_fmac_f32_e32 v22, v23, v22
	v_div_scale_f32 v23, vcc, v19, v0, v19
	v_mul_f32_e32 v24, v23, v22
	v_fma_f32 v25, -v18, v24, v23
	v_fmac_f32_e32 v24, v25, v22
	v_fma_f32 v18, -v18, v24, v23
	v_div_fmas_f32 v18, v18, v22, v24
	v_div_fixup_f32 v0, v18, v0, v19
	v_and_b32_e32 v18, 0xffff0000, v2
	v_lshlrev_b32_e32 v2, 16, v2
	v_pk_mul_f32 v[0:1], v[0:1], v[10:11]
	v_mul_f32_e32 v10, 0xbfb8aa3b, v2
	v_mul_f32_e32 v11, 0xbfb8aa3b, v18
	v_exp_f32_e32 v10, v10
	v_exp_f32_e32 v11, v11
	s_nop 0
	v_pk_add_f32 v[10:11], v[10:11], 1.0 op_sel_hi:[1,0]
	s_nop 0
	v_div_scale_f32 v19, s[22:23], v11, v11, v18
	v_rcp_f32_e32 v22, v19
	s_nop 0
	v_fma_f32 v23, -v19, v22, 1.0
	v_fmac_f32_e32 v22, v23, v22
	v_div_scale_f32 v23, vcc, v18, v11, v18
	v_mul_f32_e32 v24, v23, v22
	v_fma_f32 v25, -v19, v24, v23
	v_fmac_f32_e32 v24, v25, v22
	v_fma_f32 v19, -v19, v24, v23
	v_div_fmas_f32 v19, v19, v22, v24
	v_div_fixup_f32 v11, v19, v11, v18
	v_div_scale_f32 v18, s[22:23], v10, v10, v2
	v_rcp_f32_e32 v19, v18
	s_nop 0
	v_fma_f32 v22, -v18, v19, 1.0
	v_fmac_f32_e32 v19, v22, v19
	v_div_scale_f32 v22, vcc, v2, v10, v2
	v_mul_f32_e32 v23, v22, v19
	v_fma_f32 v24, -v18, v23, v22
	v_fmac_f32_e32 v23, v24, v19
	v_fma_f32 v18, -v18, v23, v22
	v_div_fmas_f32 v18, v18, v19, v23
	v_div_fixup_f32 v10, v18, v10, v2
	v_pk_mul_f32 v[4:5], v[10:11], v[4:5]
	v_and_b32_e32 v10, 0xffff0000, v3
	v_lshlrev_b32_e32 v11, 16, v3
	v_mul_f32_e32 v2, 0xbfb8aa3b, v11
	v_mul_f32_e32 v3, 0xbfb8aa3b, v10
	v_exp_f32_e32 v2, v2
	v_exp_f32_e32 v3, v3
	s_nop 0
	v_pk_add_f32 v[2:3], v[2:3], 1.0 op_sel_hi:[1,0]
	s_nop 0
	v_div_scale_f32 v18, s[22:23], v3, v3, v10
	v_rcp_f32_e32 v19, v18
	s_nop 0
	v_fma_f32 v22, -v18, v19, 1.0
	v_fmac_f32_e32 v19, v22, v19
	v_div_scale_f32 v22, vcc, v10, v3, v10
	v_mul_f32_e32 v23, v22, v19
	v_fma_f32 v24, -v18, v23, v22
	v_fmac_f32_e32 v23, v24, v19
	v_fma_f32 v18, -v18, v23, v22
	v_div_fmas_f32 v18, v18, v19, v23
	v_div_fixup_f32 v3, v18, v3, v10
	v_div_scale_f32 v10, s[22:23], v2, v2, v11
	v_rcp_f32_e32 v18, v10
	s_nop 0
	v_fma_f32 v19, -v10, v18, 1.0
	v_fmac_f32_e32 v18, v19, v18
	v_div_scale_f32 v19, vcc, v11, v2, v11
	v_mul_f32_e32 v22, v19, v18
	v_fma_f32 v23, -v10, v22, v19
	v_fmac_f32_e32 v22, v23, v18
	v_fma_f32 v10, -v10, v22, v19
	v_div_fmas_f32 v10, v10, v18, v22
	v_div_fixup_f32 v2, v10, v2, v11
	v_pk_mul_f32 v[2:3], v[2:3], v[6:7]
	v_cvt_pk_bf16_f32 v4, v4, v5
	v_cvt_pk_bf16_f32 v2, v2, v3
	v_mov_b32_e32 v3, v2
	v_mov_b32_e32 v2, v4
	v_lshlrev_b64 v[4:5], 12, v[14:15]
	v_lshl_add_u64 v[4:5], s[30:31], 0, v[4:5]
	v_lshl_add_u64 v[4:5], v[4:5], 0, s[70:71]
	v_lshl_add_u64 v[4:5], v[4:5], 0, v[160:161]
	v_cvt_pk_bf16_f32 v8, v8, v9
	v_cvt_pk_bf16_f32 v0, v0, v1
	v_add_co_u32_e32 v4, vcc, s36, v4
	v_mov_b32_e32 v1, v0
	v_mov_b32_e32 v0, v8
	v_addc_co_u32_e32 v5, vcc, 0, v5, vcc
	v_add_u32_e32 v18, 4, v14
	global_store_dwordx4 v[4:5], v[0:3], off offset:1024
	v_ashrrev_i32_e32 v19, 31, v18
	s_nop 0
	s_nop 0
	s_nop 0
	s_nop 0
	s_nop 0
	s_nop 1
	s_nop 0
	s_nop 0
	s_nop 0
	s_nop 0
	s_nop 0
	ds_read_b128 v[22:25], v21 offset:2112
	s_waitcnt vmcnt(9)
	v_and_b32_e32 v15, 0xffff0000, v74
	v_lshlrev_b32_e32 v4, 16, v74
	v_mul_f32_e32 v26, 0xbfb8aa3b, v4
	s_waitcnt  lgkmcnt(0)
	s_waitcnt vmcnt(7)
	v_pk_mul_f32 v[8:9], v[82:83], v[22:23]
	v_mul_f32_e32 v22, 0xbfb8aa3b, v15
	v_exp_f32_e32 v26, v26
	v_exp_f32_e32 v27, v22
	v_pk_mul_f32 v[10:11], v[84:85], v[24:25]
	v_pk_add_f32 v[22:23], v[26:27], 1.0 op_sel_hi:[1,0]
	s_nop 0
	v_div_scale_f32 v26, s[22:23], v23, v23, v15
	v_rcp_f32_e32 v27, v26
	s_nop 0
	v_fma_f32 v28, -v26, v27, 1.0
	v_fmac_f32_e32 v27, v28, v27
	v_div_scale_f32 v28, vcc, v15, v23, v15
	v_mul_f32_e32 v29, v28, v27
	v_fma_f32 v30, -v26, v29, v28
	v_fmac_f32_e32 v29, v30, v27
	v_fma_f32 v26, -v26, v29, v28
	v_div_fmas_f32 v26, v26, v27, v29
	v_div_fixup_f32 v23, v26, v23, v15
	v_div_scale_f32 v15, s[22:23], v22, v22, v4
	v_rcp_f32_e32 v26, v15
	s_nop 0
	v_fma_f32 v27, -v15, v26, 1.0
	v_fmac_f32_e32 v26, v27, v26
	v_div_scale_f32 v27, vcc, v4, v22, v4
	v_mul_f32_e32 v28, v27, v26
	v_fma_f32 v29, -v15, v28, v27
	v_fmac_f32_e32 v28, v29, v26
	v_fma_f32 v15, -v15, v28, v27
	v_div_fmas_f32 v15, v15, v26, v28
	v_div_fixup_f32 v22, v15, v22, v4
	v_pk_mul_f32 v[8:9], v[22:23], v[8:9]
	v_and_b32_e32 v15, 0xffff0000, v75
	v_lshlrev_b32_e32 v22, 16, v75
	v_mul_f32_e32 v4, 0xbfb8aa3b, v22
	v_mul_f32_e32 v5, 0xbfb8aa3b, v15
	v_exp_f32_e32 v4, v4
	v_exp_f32_e32 v5, v5
	s_nop 0
	v_pk_add_f32 v[4:5], v[4:5], 1.0 op_sel_hi:[1,0]
	s_nop 0
	v_div_scale_f32 v23, s[22:23], v5, v5, v15
	v_rcp_f32_e32 v24, v23
	s_nop 0
	v_fma_f32 v25, -v23, v24, 1.0
	v_fmac_f32_e32 v24, v25, v24
	v_div_scale_f32 v25, vcc, v15, v5, v15
	v_mul_f32_e32 v26, v25, v24
	v_fma_f32 v27, -v23, v26, v25
	v_fmac_f32_e32 v26, v27, v24
	v_fma_f32 v23, -v23, v26, v25
	v_div_fmas_f32 v23, v23, v24, v26
	v_div_fixup_f32 v5, v23, v5, v15
	v_div_scale_f32 v15, s[22:23], v4, v4, v22
	v_rcp_f32_e32 v23, v15
	s_nop 0
	v_fma_f32 v24, -v15, v23, 1.0
	v_fmac_f32_e32 v23, v24, v23
	v_div_scale_f32 v24, vcc, v22, v4, v22
	v_mul_f32_e32 v25, v24, v23
	v_fma_f32 v26, -v15, v25, v24
	v_fmac_f32_e32 v25, v26, v23
	v_fma_f32 v15, -v15, v25, v24
	v_div_fmas_f32 v15, v15, v23, v25
	v_div_fixup_f32 v4, v15, v4, v22
	v_and_b32_e32 v15, 0xffff0000, v76
	v_lshlrev_b32_e32 v6, 16, v76
	v_pk_mul_f32 v[4:5], v[4:5], v[10:11]
	v_mul_f32_e32 v10, 0xbfb8aa3b, v6
	v_mul_f32_e32 v11, 0xbfb8aa3b, v15
	ds_read_b128 v[22:25], v21 offset:2128
	v_exp_f32_e32 v10, v10
	v_exp_f32_e32 v11, v11
	s_waitcnt lgkmcnt(0)
	v_pk_mul_f32 v[0:1], v[78:79], v[22:23]
	v_pk_add_f32 v[10:11], v[10:11], 1.0 op_sel_hi:[1,0]
	v_pk_mul_f32 v[2:3], v[80:81], v[24:25]
	v_div_scale_f32 v22, s[22:23], v11, v11, v15
	v_rcp_f32_e32 v23, v22
	s_nop 0
	v_fma_f32 v26, -v22, v23, 1.0
	v_fmac_f32_e32 v23, v26, v23
	v_div_scale_f32 v26, vcc, v15, v11, v15
	v_mul_f32_e32 v27, v26, v23
	v_fma_f32 v28, -v22, v27, v26
	v_fmac_f32_e32 v27, v28, v23
	v_fma_f32 v22, -v22, v27, v26
	v_div_fmas_f32 v22, v22, v23, v27
	v_div_fixup_f32 v11, v22, v11, v15
	v_div_scale_f32 v15, s[22:23], v10, v10, v6
	v_rcp_f32_e32 v22, v15
	s_nop 0
	v_fma_f32 v23, -v15, v22, 1.0
	v_fmac_f32_e32 v22, v23, v22
	v_div_scale_f32 v23, vcc, v6, v10, v6
	v_mul_f32_e32 v26, v23, v22
	v_fma_f32 v27, -v15, v26, v23
	v_fmac_f32_e32 v26, v27, v22
	v_fma_f32 v15, -v15, v26, v23
	v_div_fmas_f32 v15, v15, v22, v26
	v_div_fixup_f32 v10, v15, v10, v6
	v_pk_mul_f32 v[0:1], v[10:11], v[0:1]
	v_and_b32_e32 v10, 0xffff0000, v77
	v_lshlrev_b32_e32 v11, 16, v77
	v_mul_f32_e32 v6, 0xbfb8aa3b, v11
	v_mul_f32_e32 v7, 0xbfb8aa3b, v10
	v_exp_f32_e32 v6, v6
	v_exp_f32_e32 v7, v7
	s_nop 0
	v_pk_add_f32 v[6:7], v[6:7], 1.0 op_sel_hi:[1,0]
	s_nop 0
	v_div_scale_f32 v15, s[22:23], v7, v7, v10
	v_rcp_f32_e32 v22, v15
	s_nop 0
	v_fma_f32 v23, -v15, v22, 1.0
	v_fmac_f32_e32 v22, v23, v22
	v_div_scale_f32 v23, vcc, v10, v7, v10
	v_mul_f32_e32 v24, v23, v22
	v_fma_f32 v25, -v15, v24, v23
	v_fmac_f32_e32 v24, v25, v22
	v_fma_f32 v15, -v15, v24, v23
	v_div_fmas_f32 v15, v15, v22, v24
	v_div_fixup_f32 v7, v15, v7, v10
	v_div_scale_f32 v10, s[22:23], v6, v6, v11
	v_rcp_f32_e32 v15, v10
	s_nop 0
	v_fma_f32 v22, -v10, v15, 1.0
	v_fmac_f32_e32 v15, v22, v15
	v_div_scale_f32 v22, vcc, v11, v6, v11
	v_mul_f32_e32 v23, v22, v15
	v_fma_f32 v24, -v10, v23, v22
	v_fmac_f32_e32 v23, v24, v15
	v_fma_f32 v10, -v10, v23, v22
	v_div_fmas_f32 v10, v10, v15, v23
	v_div_fixup_f32 v6, v10, v6, v11
	v_pk_mul_f32 v[2:3], v[6:7], v[2:3]
	v_cvt_pk_bf16_f32 v4, v4, v5
	v_cvt_pk_bf16_f32 v0, v0, v1
	v_cvt_pk_bf16_f32 v2, v2, v3
	v_mov_b32_e32 v3, v2
	v_mov_b32_e32 v2, v0
	v_mov_b32_e32 v1, v4
	v_lshlrev_b64 v[4:5], 12, v[18:19]
	v_lshl_add_u64 v[4:5], s[30:31], 0, v[4:5]
	v_lshl_add_u64 v[4:5], v[4:5], 0, s[70:71]
	v_lshl_add_u64 v[4:5], v[4:5], 0, v[160:161]
	v_cvt_pk_bf16_f32 v8, v8, v9
	v_add_co_u32_e32 v4, vcc, s36, v4
	v_mov_b32_e32 v0, v8
	s_nop 0
	v_addc_co_u32_e32 v5, vcc, 0, v5, vcc
	v_add_u32_e32 v18, 8, v14
	global_store_dwordx4 v[4:5], v[0:3], off offset:1024
	v_ashrrev_i32_e32 v19, 31, v18
	v_add_u32_e32 v14, 12, v14
	s_nop 0
	s_nop 0
	s_nop 0
	s_nop 0
	s_nop 1
	s_nop 0
	s_nop 0
	s_nop 0
	s_nop 0
	s_nop 0
	ds_read_b128 v[22:25], v21 offset:4224
	s_waitcnt vmcnt(7)
	v_and_b32_e32 v15, 0xffff0000, v112
	v_lshlrev_b32_e32 v4, 16, v112
	v_mul_f32_e32 v26, 0xbfb8aa3b, v4
	s_waitcnt  lgkmcnt(0)
	s_waitcnt vmcnt(5)
	v_pk_mul_f32 v[8:9], v[120:121], v[22:23]
	v_mul_f32_e32 v22, 0xbfb8aa3b, v15
	v_exp_f32_e32 v26, v26
	v_exp_f32_e32 v27, v22
	v_pk_mul_f32 v[10:11], v[122:123], v[24:25]
	v_pk_add_f32 v[22:23], v[26:27], 1.0 op_sel_hi:[1,0]
	s_nop 0
	v_div_scale_f32 v26, s[22:23], v23, v23, v15
	v_rcp_f32_e32 v27, v26
	s_nop 0
	v_fma_f32 v28, -v26, v27, 1.0
	v_fmac_f32_e32 v27, v28, v27
	v_div_scale_f32 v28, vcc, v15, v23, v15
	v_mul_f32_e32 v29, v28, v27
	v_fma_f32 v30, -v26, v29, v28
	v_fmac_f32_e32 v29, v30, v27
	v_fma_f32 v26, -v26, v29, v28
	v_div_fmas_f32 v26, v26, v27, v29
	v_div_fixup_f32 v23, v26, v23, v15
	v_div_scale_f32 v15, s[22:23], v22, v22, v4
	v_rcp_f32_e32 v26, v15
	s_nop 0
	v_fma_f32 v27, -v15, v26, 1.0
	v_fmac_f32_e32 v26, v27, v26
	v_div_scale_f32 v27, vcc, v4, v22, v4
	v_mul_f32_e32 v28, v27, v26
	v_fma_f32 v29, -v15, v28, v27
	v_fmac_f32_e32 v28, v29, v26
	v_fma_f32 v15, -v15, v28, v27
	v_div_fmas_f32 v15, v15, v26, v28
	v_div_fixup_f32 v22, v15, v22, v4
	v_pk_mul_f32 v[8:9], v[22:23], v[8:9]
	v_and_b32_e32 v15, 0xffff0000, v113
	v_lshlrev_b32_e32 v22, 16, v113
	v_mul_f32_e32 v4, 0xbfb8aa3b, v22
	v_mul_f32_e32 v5, 0xbfb8aa3b, v15
	v_exp_f32_e32 v4, v4
	v_exp_f32_e32 v5, v5
	s_nop 0
	v_pk_add_f32 v[4:5], v[4:5], 1.0 op_sel_hi:[1,0]
	s_nop 0
	v_div_scale_f32 v23, s[22:23], v5, v5, v15
	v_rcp_f32_e32 v24, v23
	s_nop 0
	v_fma_f32 v25, -v23, v24, 1.0
	v_fmac_f32_e32 v24, v25, v24
	v_div_scale_f32 v25, vcc, v15, v5, v15
	v_mul_f32_e32 v26, v25, v24
	v_fma_f32 v27, -v23, v26, v25
	v_fmac_f32_e32 v26, v27, v24
	v_fma_f32 v23, -v23, v26, v25
	v_div_fmas_f32 v23, v23, v24, v26
	v_div_fixup_f32 v5, v23, v5, v15
	v_div_scale_f32 v15, s[22:23], v4, v4, v22
	v_rcp_f32_e32 v23, v15
	s_nop 0
	v_fma_f32 v24, -v15, v23, 1.0
	v_fmac_f32_e32 v23, v24, v23
	v_div_scale_f32 v24, vcc, v22, v4, v22
	v_mul_f32_e32 v25, v24, v23
	v_fma_f32 v26, -v15, v25, v24
	v_fmac_f32_e32 v25, v26, v23
	v_fma_f32 v15, -v15, v25, v24
	v_div_fmas_f32 v15, v15, v23, v25
	v_div_fixup_f32 v4, v15, v4, v22
	v_and_b32_e32 v15, 0xffff0000, v114
	v_lshlrev_b32_e32 v6, 16, v114
	v_pk_mul_f32 v[4:5], v[4:5], v[10:11]
	v_mul_f32_e32 v10, 0xbfb8aa3b, v6
	v_mul_f32_e32 v11, 0xbfb8aa3b, v15
	ds_read_b128 v[22:25], v21 offset:4240
	v_exp_f32_e32 v10, v10
	v_exp_f32_e32 v11, v11
	s_waitcnt lgkmcnt(0)
	v_pk_mul_f32 v[0:1], v[116:117], v[22:23]
	v_pk_add_f32 v[10:11], v[10:11], 1.0 op_sel_hi:[1,0]
	v_pk_mul_f32 v[2:3], v[118:119], v[24:25]
	v_div_scale_f32 v22, s[22:23], v11, v11, v15
	v_rcp_f32_e32 v23, v22
	s_nop 0
	v_fma_f32 v26, -v22, v23, 1.0
	v_fmac_f32_e32 v23, v26, v23
	v_div_scale_f32 v26, vcc, v15, v11, v15
	v_mul_f32_e32 v27, v26, v23
	v_fma_f32 v28, -v22, v27, v26
	v_fmac_f32_e32 v27, v28, v23
	v_fma_f32 v22, -v22, v27, v26
	v_div_fmas_f32 v22, v22, v23, v27
	v_div_fixup_f32 v11, v22, v11, v15
	v_div_scale_f32 v15, s[22:23], v10, v10, v6
	v_rcp_f32_e32 v22, v15
	s_nop 0
	v_fma_f32 v23, -v15, v22, 1.0
	v_fmac_f32_e32 v22, v23, v22
	v_div_scale_f32 v23, vcc, v6, v10, v6
	v_mul_f32_e32 v26, v23, v22
	v_fma_f32 v27, -v15, v26, v23
	v_fmac_f32_e32 v26, v27, v22
	v_fma_f32 v15, -v15, v26, v23
	v_div_fmas_f32 v15, v15, v22, v26
	v_div_fixup_f32 v10, v15, v10, v6
	v_pk_mul_f32 v[0:1], v[10:11], v[0:1]
	v_and_b32_e32 v10, 0xffff0000, v115
	v_lshlrev_b32_e32 v11, 16, v115
	v_mul_f32_e32 v6, 0xbfb8aa3b, v11
	v_mul_f32_e32 v7, 0xbfb8aa3b, v10
	v_exp_f32_e32 v6, v6
	v_exp_f32_e32 v7, v7
	s_nop 0
	v_pk_add_f32 v[6:7], v[6:7], 1.0 op_sel_hi:[1,0]
	s_nop 0
	v_div_scale_f32 v15, s[22:23], v7, v7, v10
	v_rcp_f32_e32 v22, v15
	s_nop 0
	v_fma_f32 v23, -v15, v22, 1.0
	v_fmac_f32_e32 v22, v23, v22
	v_div_scale_f32 v23, vcc, v10, v7, v10
	v_mul_f32_e32 v24, v23, v22
	v_fma_f32 v25, -v15, v24, v23
	v_fmac_f32_e32 v24, v25, v22
	v_fma_f32 v15, -v15, v24, v23
	v_div_fmas_f32 v15, v15, v22, v24
	v_div_fixup_f32 v7, v15, v7, v10
	v_div_scale_f32 v10, s[22:23], v6, v6, v11
	v_rcp_f32_e32 v15, v10
	s_nop 0
	v_fma_f32 v22, -v10, v15, 1.0
	v_fmac_f32_e32 v15, v22, v15
	v_div_scale_f32 v22, vcc, v11, v6, v11
	v_mul_f32_e32 v23, v22, v15
	v_fma_f32 v24, -v10, v23, v22
	v_fmac_f32_e32 v23, v24, v15
	v_fma_f32 v10, -v10, v23, v22
	v_div_fmas_f32 v10, v10, v15, v23
	v_div_fixup_f32 v6, v10, v6, v11
	v_pk_mul_f32 v[2:3], v[6:7], v[2:3]
	v_cvt_pk_bf16_f32 v4, v4, v5
	v_cvt_pk_bf16_f32 v0, v0, v1
	v_cvt_pk_bf16_f32 v2, v2, v3
	v_mov_b32_e32 v3, v2
	v_mov_b32_e32 v2, v0
	v_mov_b32_e32 v1, v4
	v_lshlrev_b64 v[4:5], 12, v[18:19]
	v_lshl_add_u64 v[4:5], s[30:31], 0, v[4:5]
	v_lshl_add_u64 v[4:5], v[4:5], 0, s[70:71]
	v_lshl_add_u64 v[4:5], v[4:5], 0, v[160:161]
	v_cvt_pk_bf16_f32 v8, v8, v9
	v_add_co_u32_e32 v4, vcc, s36, v4
	v_mov_b32_e32 v0, v8
	s_nop 0
	v_addc_co_u32_e32 v5, vcc, 0, v5, vcc
	global_store_dwordx4 v[4:5], v[0:3], off offset:1024
	v_ashrrev_i32_e32 v15, 31, v14
	s_nop 0
	s_nop 0
	s_nop 0
	s_nop 0
	s_nop 0
	s_nop 1
	s_nop 0
	s_nop 0
	s_nop 0
	s_nop 0
	s_nop 0
	ds_read_b128 v[16:19], v21 offset:6336
	ds_read_b128 v[22:25], v21 offset:6352
	v_add_u32_e32 v21, 0x2100, v21
	s_waitcnt vmcnt(5)
	v_and_b32_e32 v28, 0xffff0000, v134
	v_lshlrev_b32_e32 v4, 16, v134
	v_mul_f32_e32 v26, 0xbfb8aa3b, v4
	s_waitcnt  lgkmcnt(1)
	s_waitcnt vmcnt(3)
	v_pk_mul_f32 v[8:9], v[142:143], v[16:17]
	v_mul_f32_e32 v16, 0xbfb8aa3b, v28
	v_exp_f32_e32 v26, v26
	v_exp_f32_e32 v27, v16
	v_pk_mul_f32 v[10:11], v[144:145], v[18:19]
	s_waitcnt lgkmcnt(0)
	v_pk_mul_f32 v[0:1], v[138:139], v[22:23]
	v_pk_mul_f32 v[2:3], v[140:141], v[24:25]
	v_pk_add_f32 v[16:17], v[26:27], 1.0 op_sel_hi:[1,0]
	s_nop 0
	v_div_scale_f32 v26, s[22:23], v17, v17, v28
	v_rcp_f32_e32 v27, v26
	s_nop 0
	v_fma_f32 v29, -v26, v27, 1.0
	v_fmac_f32_e32 v27, v29, v27
	v_div_scale_f32 v29, vcc, v28, v17, v28
	v_mul_f32_e32 v30, v29, v27
	v_fma_f32 v31, -v26, v30, v29
	v_fmac_f32_e32 v30, v31, v27
	v_fma_f32 v26, -v26, v30, v29
	v_div_fmas_f32 v26, v26, v27, v30
	v_div_fixup_f32 v17, v26, v17, v28
	v_div_scale_f32 v26, s[22:23], v16, v16, v4
	v_rcp_f32_e32 v27, v26
	s_nop 0
	v_fma_f32 v28, -v26, v27, 1.0
	v_fmac_f32_e32 v27, v28, v27
	v_div_scale_f32 v28, vcc, v4, v16, v4
	v_mul_f32_e32 v29, v28, v27
	v_fma_f32 v30, -v26, v29, v28
	v_fmac_f32_e32 v29, v30, v27
	v_fma_f32 v26, -v26, v29, v28
	v_div_fmas_f32 v26, v26, v27, v29
	v_div_fixup_f32 v16, v26, v16, v4
	v_pk_mul_f32 v[8:9], v[16:17], v[8:9]
	v_and_b32_e32 v16, 0xffff0000, v135
	v_lshlrev_b32_e32 v17, 16, v135
	v_mul_f32_e32 v4, 0xbfb8aa3b, v17
	v_mul_f32_e32 v5, 0xbfb8aa3b, v16
	v_exp_f32_e32 v4, v4
	v_exp_f32_e32 v5, v5
	s_nop 0
	v_pk_add_f32 v[4:5], v[4:5], 1.0 op_sel_hi:[1,0]
	s_nop 0
	v_div_scale_f32 v18, s[22:23], v5, v5, v16
	v_rcp_f32_e32 v19, v18
	s_nop 0
	v_fma_f32 v26, -v18, v19, 1.0
	v_fmac_f32_e32 v19, v26, v19
	v_div_scale_f32 v26, vcc, v16, v5, v16
	v_mul_f32_e32 v27, v26, v19
	v_fma_f32 v28, -v18, v27, v26
	v_fmac_f32_e32 v27, v28, v19
	v_fma_f32 v18, -v18, v27, v26
	v_div_fmas_f32 v18, v18, v19, v27
	v_div_fixup_f32 v5, v18, v5, v16
	v_div_scale_f32 v16, s[22:23], v4, v4, v17
	v_rcp_f32_e32 v18, v16
	s_nop 0
	v_fma_f32 v19, -v16, v18, 1.0
	v_fmac_f32_e32 v18, v19, v18
	v_div_scale_f32 v19, vcc, v17, v4, v17
	v_mul_f32_e32 v26, v19, v18
	v_fma_f32 v27, -v16, v26, v19
	v_fmac_f32_e32 v26, v27, v18
	v_fma_f32 v16, -v16, v26, v19
	v_div_fmas_f32 v16, v16, v18, v26
	v_div_fixup_f32 v4, v16, v4, v17
	v_and_b32_e32 v16, 0xffff0000, v136
	v_lshlrev_b32_e32 v6, 16, v136
	v_pk_mul_f32 v[4:5], v[4:5], v[10:11]
	v_mul_f32_e32 v10, 0xbfb8aa3b, v6
	v_mul_f32_e32 v11, 0xbfb8aa3b, v16
	v_exp_f32_e32 v10, v10
	v_exp_f32_e32 v11, v11
	s_nop 0
	v_pk_add_f32 v[10:11], v[10:11], 1.0 op_sel_hi:[1,0]
	s_nop 0
	v_div_scale_f32 v17, s[22:23], v11, v11, v16
	v_rcp_f32_e32 v18, v17
	s_nop 0
	v_fma_f32 v19, -v17, v18, 1.0
	v_fmac_f32_e32 v18, v19, v18
	v_div_scale_f32 v19, vcc, v16, v11, v16
	v_mul_f32_e32 v22, v19, v18
	v_fma_f32 v23, -v17, v22, v19
	v_fmac_f32_e32 v22, v23, v18
	v_fma_f32 v17, -v17, v22, v19
	v_div_fmas_f32 v17, v17, v18, v22
	v_div_fixup_f32 v11, v17, v11, v16
	v_div_scale_f32 v16, s[22:23], v10, v10, v6
	v_rcp_f32_e32 v17, v16
	s_nop 0
	v_fma_f32 v18, -v16, v17, 1.0
	v_fmac_f32_e32 v17, v18, v17
	v_div_scale_f32 v18, vcc, v6, v10, v6
	v_mul_f32_e32 v19, v18, v17
	v_fma_f32 v22, -v16, v19, v18
	v_fmac_f32_e32 v19, v22, v17
	v_fma_f32 v16, -v16, v19, v18
	v_div_fmas_f32 v16, v16, v17, v19
	v_div_fixup_f32 v10, v16, v10, v6
	v_pk_mul_f32 v[0:1], v[10:11], v[0:1]
	v_and_b32_e32 v10, 0xffff0000, v137
	v_lshlrev_b32_e32 v11, 16, v137
	v_mul_f32_e32 v6, 0xbfb8aa3b, v11
	v_mul_f32_e32 v7, 0xbfb8aa3b, v10
	v_exp_f32_e32 v6, v6
	v_exp_f32_e32 v7, v7
	s_nop 0
	v_pk_add_f32 v[6:7], v[6:7], 1.0 op_sel_hi:[1,0]
	s_nop 0
	v_div_scale_f32 v16, s[22:23], v7, v7, v10
	v_rcp_f32_e32 v17, v16
	s_nop 0
	v_fma_f32 v18, -v16, v17, 1.0
	v_fmac_f32_e32 v17, v18, v17
	v_div_scale_f32 v18, vcc, v10, v7, v10
	v_mul_f32_e32 v19, v18, v17
	v_fma_f32 v22, -v16, v19, v18
	v_fmac_f32_e32 v19, v22, v17
	v_fma_f32 v16, -v16, v19, v18
	v_div_fmas_f32 v16, v16, v17, v19
	v_div_fixup_f32 v7, v16, v7, v10
	v_div_scale_f32 v10, s[22:23], v6, v6, v11
	v_rcp_f32_e32 v16, v10
	s_nop 0
	v_fma_f32 v17, -v10, v16, 1.0
	v_fmac_f32_e32 v16, v17, v16
	v_div_scale_f32 v17, vcc, v11, v6, v11
	v_mul_f32_e32 v18, v17, v16
	v_fma_f32 v19, -v10, v18, v17
	v_fmac_f32_e32 v18, v19, v16
	v_fma_f32 v10, -v10, v18, v17
	v_div_fmas_f32 v10, v10, v16, v18
	v_div_fixup_f32 v6, v10, v6, v11
	v_pk_mul_f32 v[2:3], v[6:7], v[2:3]
	v_cvt_pk_bf16_f32 v4, v4, v5
	v_cvt_pk_bf16_f32 v0, v0, v1
	v_cvt_pk_bf16_f32 v2, v2, v3
	v_mov_b32_e32 v3, v2
	v_mov_b32_e32 v2, v0
	v_mov_b32_e32 v1, v4
	v_lshlrev_b64 v[4:5], 12, v[14:15]
	v_lshl_add_u64 v[4:5], s[30:31], 0, v[4:5]
	v_lshl_add_u64 v[4:5], v[4:5], 0, s[70:71]
	v_lshl_add_u64 v[4:5], v[4:5], 0, v[160:161]
	v_cvt_pk_bf16_f32 v8, v8, v9
	v_add_co_u32_e32 v4, vcc, 0xcc00000, v4
	v_mov_b32_e32 v0, v8
	s_nop 0
	v_addc_co_u32_e32 v5, vcc, 0, v5, vcc
	global_store_dwordx4 v[4:5], v[0:3], off offset:1024
	s_cbranch_scc1 .LBB0_670
	s_barrier

.LBB0_693:
	s_nop 0
	v_lshl_add_u64 v[0:1], v[26:27], 0, s[36:37]
	global_load_dword v28, v[0:1], off
	v_lshl_add_u64 v[0:1], v[24:25], 0, v[160:161]
	v_add_co_u32_e32 v4, vcc, 0x6400000, v0
	v_lshl_add_u64 v[24:25], v[24:25], 0, s[40:41]
	s_nop 0
	v_addc_co_u32_e32 v5, vcc, 0, v1, vcc
	global_load_dwordx4 v[0:3], v[4:5], off
	s_nop 0
	global_load_dwordx4 v[4:7], v[4:5], off offset:2048
	ds_read_b128 v[32:35], v31
	ds_read_b128 v[36:39], v31 offset:16
	s_waitcnt vmcnt(3)
	v_lshl_add_u64 v[64:65], v[20:21], 0, s[36:37]
	global_load_dword v66, v[64:65], off offset:16
	v_lshl_add_u64 v[70:71], v[18:19], 0, v[160:161]
	v_add_co_u32_e32 v68, vcc, s22, v70
	s_nop 1
	v_addc_co_u32_e32 v69, vcc, 0, v71, vcc
	global_load_dwordx4 v[72:75], v[68:69], off
	global_load_dwordx4 v[76:79], v[68:69], off offset:2048
	global_load_dword v67, v[64:65], off offset:32
	v_lshl_add_u64 v[82:83], v[14:15], 0, v[160:161]
	v_add_co_u32_e32 v80, vcc, s22, v82
	s_nop 1
	v_addc_co_u32_e32 v81, vcc, 0, v83, vcc
	global_load_dwordx4 v[84:87], v[80:81], off
	global_load_dwordx4 v[88:91], v[80:81], off offset:2048
	global_load_dword v92, v[64:65], off offset:48
	v_lshl_add_u64 v[112:113], v[10:11], 0, v[160:161]
	v_add_co_u32_e32 v110, vcc, s22, v112
	s_nop 1
	v_addc_co_u32_e32 v111, vcc, 0, v113, vcc
	global_load_dwordx4 v[114:117], v[110:111], off
	global_load_dwordx4 v[118:121], v[110:111], off offset:2048
	s_waitcnt vmcnt(9)
	v_and_b32_e32 v29, 0xffff0000, v4
	v_lshlrev_b32_e32 v4, 16, v4
	v_mul_f32_e32 v30, 0xbfb8aa3b, v4
	v_exp_f32_e32 v40, v30
	v_mul_f32_e32 v30, 0xbfb8aa3b, v29
	v_exp_f32_e32 v41, v30
	s_nop 0
	v_pk_add_f32 v[40:41], v[40:41], 1.0 op_sel_hi:[1,0]
	s_nop 0
	v_div_scale_f32 v30, s[20:21], v41, v41, v29
	v_rcp_f32_e32 v42, v30
	s_nop 0
	v_fma_f32 v43, -v30, v42, 1.0
	v_fmac_f32_e32 v42, v43, v42
	v_div_scale_f32 v43, vcc, v29, v41, v29
	v_mul_f32_e32 v44, v43, v42
	v_fma_f32 v45, -v30, v44, v43
	v_fmac_f32_e32 v44, v45, v42
	v_fma_f32 v30, -v30, v44, v43
	v_div_fmas_f32 v30, v30, v42, v44
	v_div_fixup_f32 v41, v30, v41, v29
	v_div_scale_f32 v29, s[20:21], v40, v40, v4
	v_rcp_f32_e32 v30, v29
	s_nop 0
	v_fma_f32 v42, -v29, v30, 1.0
	v_fmac_f32_e32 v30, v42, v30
	v_div_scale_f32 v42, vcc, v4, v40, v4
	v_mul_f32_e32 v43, v42, v30
	v_fma_f32 v44, -v29, v43, v42
	v_fmac_f32_e32 v43, v44, v30
	v_fma_f32 v29, -v29, v43, v42
	v_div_fmas_f32 v29, v29, v30, v43
	v_div_fixup_f32 v40, v29, v40, v4
	v_and_b32_e32 v43, 0xffff0000, v0
	v_lshlrev_b32_e32 v42, 16, v0
	s_waitcnt lgkmcnt(1)
	v_add_f32_e32 v32, v28, v32
	v_add_f32_e32 v33, v28, v33
	v_and_b32_e32 v0, 0xffff0000, v5
	v_lshlrev_b32_e32 v29, 16, v5
	v_mul_f32_e32 v4, 0xbfb8aa3b, v29
	v_mul_f32_e32 v5, 0xbfb8aa3b, v0
	v_exp_f32_e32 v4, v4
	v_exp_f32_e32 v5, v5
	v_pk_mul_f32 v[40:41], v[40:41], v[42:43]
	v_pk_add_f32 v[4:5], v[4:5], 1.0 op_sel_hi:[1,0]
	s_nop 0
	v_div_scale_f32 v30, s[20:21], v5, v5, v0
	v_pk_mul_f32 v[32:33], v[32:33], v[40:41]
	v_rcp_f32_e32 v40, v30
	s_nop 0
	v_fma_f32 v41, -v30, v40, 1.0
	v_fmac_f32_e32 v40, v41, v40
	v_div_scale_f32 v41, vcc, v0, v5, v0
	v_mul_f32_e32 v42, v41, v40
	v_fma_f32 v43, -v30, v42, v41
	v_fmac_f32_e32 v42, v43, v40
	v_fma_f32 v30, -v30, v42, v41
	v_div_fmas_f32 v30, v30, v40, v42
	v_div_fixup_f32 v5, v30, v5, v0
	v_div_scale_f32 v0, s[20:21], v4, v4, v29
	v_rcp_f32_e32 v30, v0
	s_nop 0
	v_fma_f32 v40, -v0, v30, 1.0
	v_fmac_f32_e32 v30, v40, v30
	v_div_scale_f32 v40, vcc, v29, v4, v29
	v_mul_f32_e32 v41, v40, v30
	v_fma_f32 v42, -v0, v41, v40
	v_fmac_f32_e32 v41, v42, v30
	v_fma_f32 v0, -v0, v41, v40
	v_div_fmas_f32 v0, v0, v30, v41
	v_div_fixup_f32 v4, v0, v4, v29
	v_and_b32_e32 v41, 0xffff0000, v1
	v_lshlrev_b32_e32 v40, 16, v1
	v_pk_mul_f32 v[0:1], v[4:5], v[40:41]
	v_add_f32_e32 v4, v28, v34
	v_add_f32_e32 v5, v28, v35
	v_and_b32_e32 v29, 0xffff0000, v6
	v_lshlrev_b32_e32 v6, 16, v6
	v_pk_mul_f32 v[0:1], v[4:5], v[0:1]
	v_mul_f32_e32 v4, 0xbfb8aa3b, v6
	v_mul_f32_e32 v5, 0xbfb8aa3b, v29
	v_exp_f32_e32 v4, v4
	v_exp_f32_e32 v5, v5
	s_nop 0
	v_pk_add_f32 v[4:5], v[4:5], 1.0 op_sel_hi:[1,0]
	s_nop 0
	v_div_scale_f32 v30, s[20:21], v5, v5, v29
	v_rcp_f32_e32 v34, v30
	s_nop 0
	v_fma_f32 v35, -v30, v34, 1.0
	v_fmac_f32_e32 v34, v35, v34
	v_div_scale_f32 v35, vcc, v29, v5, v29
	v_mul_f32_e32 v40, v35, v34
	v_fma_f32 v41, -v30, v40, v35
	v_fmac_f32_e32 v40, v41, v34
	v_fma_f32 v30, -v30, v40, v35
	v_div_fmas_f32 v30, v30, v34, v40
	v_div_fixup_f32 v5, v30, v5, v29
	v_div_scale_f32 v29, s[20:21], v4, v4, v6
	v_rcp_f32_e32 v30, v29
	s_nop 0
	v_fma_f32 v34, -v29, v30, 1.0
	v_fmac_f32_e32 v30, v34, v30
	v_div_scale_f32 v34, vcc, v6, v4, v6
	v_mul_f32_e32 v35, v34, v30
	v_fma_f32 v40, -v29, v35, v34
	v_fmac_f32_e32 v35, v40, v30
	v_fma_f32 v29, -v29, v35, v34
	v_div_fmas_f32 v29, v29, v30, v35
	v_div_fixup_f32 v4, v29, v4, v6
	v_and_b32_e32 v35, 0xffff0000, v2
	v_lshlrev_b32_e32 v34, 16, v2
	v_pk_mul_f32 v[4:5], v[4:5], v[34:35]
	s_waitcnt lgkmcnt(0)
	v_add_f32_e32 v34, v28, v36
	v_add_f32_e32 v35, v28, v37
	v_and_b32_e32 v2, 0xffff0000, v7
	v_lshlrev_b32_e32 v29, 16, v7
	v_mul_f32_e32 v6, 0xbfb8aa3b, v29
	v_mul_f32_e32 v7, 0xbfb8aa3b, v2
	v_exp_f32_e32 v6, v6
	v_exp_f32_e32 v7, v7
	v_pk_mul_f32 v[4:5], v[34:35], v[4:5]
	v_pk_add_f32 v[6:7], v[6:7], 1.0 op_sel_hi:[1,0]
	s_nop 0
	v_div_scale_f32 v30, s[20:21], v7, v7, v2
	v_rcp_f32_e32 v34, v30
	s_nop 0
	v_fma_f32 v35, -v30, v34, 1.0
	v_fmac_f32_e32 v34, v35, v34
	v_div_scale_f32 v35, vcc, v2, v7, v2
	v_mul_f32_e32 v36, v35, v34
	v_fma_f32 v37, -v30, v36, v35
	v_fmac_f32_e32 v36, v37, v34
	v_fma_f32 v30, -v30, v36, v35
	v_div_fmas_f32 v30, v30, v34, v36
	v_div_fixup_f32 v7, v30, v7, v2
	v_div_scale_f32 v2, s[20:21], v6, v6, v29
	v_rcp_f32_e32 v30, v2
	s_nop 0
	v_fma_f32 v34, -v2, v30, 1.0
	v_fmac_f32_e32 v30, v34, v30
	v_div_scale_f32 v34, vcc, v29, v6, v29
	v_mul_f32_e32 v35, v34, v30
	v_fma_f32 v36, -v2, v35, v34
	v_fmac_f32_e32 v35, v36, v30
	v_fma_f32 v2, -v2, v35, v34
	v_div_fmas_f32 v2, v2, v30, v35
	v_div_fixup_f32 v6, v2, v6, v29
	v_and_b32_e32 v35, 0xffff0000, v3
	v_lshlrev_b32_e32 v34, 16, v3
	v_pk_mul_f32 v[2:3], v[6:7], v[34:35]
	v_add_f32_e32 v6, v28, v38
	v_add_f32_e32 v7, v28, v39
	v_pk_mul_f32 v[2:3], v[6:7], v[2:3]
	v_cvt_pk_bf16_f32 v32, v32, v33
	v_cvt_pk_bf16_f32 v0, v0, v1
	v_cvt_pk_bf16_f32 v4, v4, v5
	v_cvt_pk_bf16_f32 v2, v2, v3
	v_mov_b32_e32 v3, v2
	v_mov_b32_e32 v2, v4
	v_mov_b32_e32 v1, v0
	v_mov_b32_e32 v0, v32
	v_lshl_add_u64 v[4:5], v[22:23], 0, v[160:161]
	global_store_dwordx4 v[4:5], v[0:3], off
	v_lshl_add_u64 v[28:29], v[20:21], 0, s[36:37]
	s_nop 0
	s_nop 0
	s_nop 0
	s_add_u32 s36, s36, 64
	s_nop 0
	s_nop 0
	s_nop 0
	s_nop 0
	s_nop 0
	ds_read_b128 v[32:35], v31 offset:2112
	s_addc_u32 s37, s37, 0
	v_lshl_add_u64 v[18:19], v[18:19], 0, s[40:41]
	v_lshl_add_u64 v[22:23], v[22:23], 0, s[38:39]
	s_cmpk_lg_i32 s36, 0x80
	s_waitcnt  lgkmcnt(0)
	s_waitcnt vmcnt(9)
	v_add_f32_e32 v32, v66, v32
	v_add_f32_e32 v33, v66, v33
	s_waitcnt vmcnt(7)
	v_and_b32_e32 v38, 0xffff0000, v76
	v_lshlrev_b32_e32 v4, 16, v76
	v_mul_f32_e32 v36, 0xbfb8aa3b, v4
	v_mul_f32_e32 v37, 0xbfb8aa3b, v38
	v_exp_f32_e32 v36, v36
	v_exp_f32_e32 v37, v37
	s_nop 0
	v_pk_add_f32 v[36:37], v[36:37], 1.0 op_sel_hi:[1,0]
	s_nop 0
	v_div_scale_f32 v39, s[20:21], v37, v37, v38
	v_rcp_f32_e32 v40, v39
	s_nop 0
	v_fma_f32 v41, -v39, v40, 1.0
	v_fmac_f32_e32 v40, v41, v40
	v_div_scale_f32 v41, vcc, v38, v37, v38
	v_mul_f32_e32 v42, v41, v40
	v_fma_f32 v43, -v39, v42, v41
	v_fmac_f32_e32 v42, v43, v40
	v_fma_f32 v39, -v39, v42, v41
	v_div_fmas_f32 v39, v39, v40, v42
	v_div_fixup_f32 v37, v39, v37, v38
	v_div_scale_f32 v38, s[20:21], v36, v36, v4
	v_rcp_f32_e32 v39, v38
	s_nop 0
	v_fma_f32 v40, -v38, v39, 1.0
	v_fmac_f32_e32 v39, v40, v39
	v_div_scale_f32 v40, vcc, v4, v36, v4
	v_mul_f32_e32 v41, v40, v39
	v_fma_f32 v42, -v38, v41, v40
	v_fmac_f32_e32 v41, v42, v39
	v_fma_f32 v38, -v38, v41, v40
	v_div_fmas_f32 v38, v38, v39, v41
	v_div_fixup_f32 v36, v38, v36, v4
	v_and_b32_e32 v39, 0xffff0000, v72
	v_lshlrev_b32_e32 v38, 16, v72
	v_pk_mul_f32 v[36:37], v[36:37], v[38:39]
	v_and_b32_e32 v0, 0xffff0000, v77
	v_pk_mul_f32 v[32:33], v[32:33], v[36:37]
	v_lshlrev_b32_e32 v36, 16, v77
	v_mul_f32_e32 v4, 0xbfb8aa3b, v36
	v_mul_f32_e32 v5, 0xbfb8aa3b, v0
	v_exp_f32_e32 v4, v4
	v_exp_f32_e32 v5, v5
	s_nop 0
	v_pk_add_f32 v[4:5], v[4:5], 1.0 op_sel_hi:[1,0]
	s_nop 0
	v_div_scale_f32 v37, s[20:21], v5, v5, v0
	v_rcp_f32_e32 v38, v37
	s_nop 0
	v_fma_f32 v39, -v37, v38, 1.0
	v_fmac_f32_e32 v38, v39, v38
	v_div_scale_f32 v39, vcc, v0, v5, v0
	v_mul_f32_e32 v40, v39, v38
	v_fma_f32 v41, -v37, v40, v39
	v_fmac_f32_e32 v40, v41, v38
	v_fma_f32 v37, -v37, v40, v39
	v_div_fmas_f32 v37, v37, v38, v40
	v_div_fixup_f32 v5, v37, v5, v0
	v_div_scale_f32 v0, s[20:21], v4, v4, v36
	v_rcp_f32_e32 v37, v0
	s_nop 0
	v_fma_f32 v38, -v0, v37, 1.0
	v_fmac_f32_e32 v37, v38, v37
	v_div_scale_f32 v38, vcc, v36, v4, v36
	v_mul_f32_e32 v39, v38, v37
	v_fma_f32 v40, -v0, v39, v38
	v_fmac_f32_e32 v39, v40, v37
	v_fma_f32 v0, -v0, v39, v38
	v_div_fmas_f32 v0, v0, v37, v39
	v_div_fixup_f32 v4, v0, v4, v36
	v_and_b32_e32 v37, 0xffff0000, v73
	v_lshlrev_b32_e32 v36, 16, v73
	v_pk_mul_f32 v[0:1], v[4:5], v[36:37]
	v_add_f32_e32 v4, v66, v34
	v_add_f32_e32 v5, v66, v35
	v_and_b32_e32 v38, 0xffff0000, v78
	v_lshlrev_b32_e32 v6, 16, v78
	v_pk_mul_f32 v[0:1], v[4:5], v[0:1]
	v_mul_f32_e32 v4, 0xbfb8aa3b, v6
	v_mul_f32_e32 v5, 0xbfb8aa3b, v38
	v_exp_f32_e32 v4, v4
	v_exp_f32_e32 v5, v5
	ds_read_b128 v[34:37], v31 offset:2128
	v_pk_add_f32 v[4:5], v[4:5], 1.0 op_sel_hi:[1,0]
	s_nop 0
	v_div_scale_f32 v39, s[20:21], v5, v5, v38
	v_rcp_f32_e32 v40, v39
	s_waitcnt lgkmcnt(0)
	v_add_f32_e32 v34, v66, v34
	v_add_f32_e32 v35, v66, v35
	v_fma_f32 v41, -v39, v40, 1.0
	v_fmac_f32_e32 v40, v41, v40
	v_div_scale_f32 v41, vcc, v38, v5, v38
	v_mul_f32_e32 v42, v41, v40
	v_fma_f32 v43, -v39, v42, v41
	v_fmac_f32_e32 v42, v43, v40
	v_fma_f32 v39, -v39, v42, v41
	v_div_fmas_f32 v39, v39, v40, v42
	v_div_fixup_f32 v5, v39, v5, v38
	v_div_scale_f32 v38, s[20:21], v4, v4, v6
	v_rcp_f32_e32 v39, v38
	s_nop 0
	v_fma_f32 v40, -v38, v39, 1.0
	v_fmac_f32_e32 v39, v40, v39
	v_div_scale_f32 v40, vcc, v6, v4, v6
	v_mul_f32_e32 v41, v40, v39
	v_fma_f32 v42, -v38, v41, v40
	v_fmac_f32_e32 v41, v42, v39
	v_fma_f32 v38, -v38, v41, v40
	v_div_fmas_f32 v38, v38, v39, v41
	v_div_fixup_f32 v4, v38, v4, v6
	v_and_b32_e32 v39, 0xffff0000, v74
	v_lshlrev_b32_e32 v38, 16, v74
	v_pk_mul_f32 v[4:5], v[4:5], v[38:39]
	v_and_b32_e32 v2, 0xffff0000, v79
	v_pk_mul_f32 v[4:5], v[34:35], v[4:5]
	v_lshlrev_b32_e32 v34, 16, v79
	v_mul_f32_e32 v6, 0xbfb8aa3b, v34
	v_mul_f32_e32 v7, 0xbfb8aa3b, v2
	v_exp_f32_e32 v6, v6
	v_exp_f32_e32 v7, v7
	s_nop 0
	v_pk_add_f32 v[6:7], v[6:7], 1.0 op_sel_hi:[1,0]
	s_nop 0
	v_div_scale_f32 v35, s[20:21], v7, v7, v2
	v_rcp_f32_e32 v38, v35
	s_nop 0
	v_fma_f32 v39, -v35, v38, 1.0
	v_fmac_f32_e32 v38, v39, v38
	v_div_scale_f32 v39, vcc, v2, v7, v2
	v_mul_f32_e32 v40, v39, v38
	v_fma_f32 v41, -v35, v40, v39
	v_fmac_f32_e32 v40, v41, v38
	v_fma_f32 v35, -v35, v40, v39
	v_div_fmas_f32 v35, v35, v38, v40
	v_div_fixup_f32 v7, v35, v7, v2
	v_div_scale_f32 v2, s[20:21], v6, v6, v34
	v_rcp_f32_e32 v35, v2
	s_nop 0
	v_fma_f32 v38, -v2, v35, 1.0
	v_fmac_f32_e32 v35, v38, v35
	v_div_scale_f32 v38, vcc, v34, v6, v34
	v_mul_f32_e32 v39, v38, v35
	v_fma_f32 v40, -v2, v39, v38
	v_fmac_f32_e32 v39, v40, v35
	v_fma_f32 v2, -v2, v39, v38
	v_div_fmas_f32 v2, v2, v35, v39
	v_div_fixup_f32 v6, v2, v6, v34
	v_and_b32_e32 v35, 0xffff0000, v75
	v_lshlrev_b32_e32 v34, 16, v75
	v_pk_mul_f32 v[2:3], v[6:7], v[34:35]
	v_add_f32_e32 v6, v66, v36
	v_add_f32_e32 v7, v66, v37
	v_pk_mul_f32 v[2:3], v[6:7], v[2:3]
	v_cvt_pk_bf16_f32 v32, v32, v33
	v_cvt_pk_bf16_f32 v0, v0, v1
	v_cvt_pk_bf16_f32 v4, v4, v5
	v_cvt_pk_bf16_f32 v2, v2, v3
	v_mov_b32_e32 v3, v2
	v_mov_b32_e32 v2, v4
	v_mov_b32_e32 v1, v0
	v_mov_b32_e32 v0, v32
	v_lshl_add_u64 v[4:5], v[16:17], 0, v[160:161]
	global_store_dwordx4 v[4:5], v[0:3], off
	s_nop 0
	v_lshl_add_u64 v[16:17], v[16:17], 0, s[38:39]
	s_nop 0
	s_nop 0
	v_lshl_add_u64 v[14:15], v[14:15], 0, s[40:41]
	s_nop 0
	s_nop 0
	s_nop 0
	s_nop 0
	s_nop 0
	ds_read_b128 v[32:35], v31 offset:4224
	s_waitcnt  lgkmcnt(0)
	s_waitcnt vmcnt(7)
	v_add_f32_e32 v32, v67, v32
	v_add_f32_e32 v33, v67, v33
	s_waitcnt vmcnt(5)
	v_and_b32_e32 v38, 0xffff0000, v88
	v_lshlrev_b32_e32 v4, 16, v88
	v_mul_f32_e32 v36, 0xbfb8aa3b, v4
	v_mul_f32_e32 v37, 0xbfb8aa3b, v38
	v_exp_f32_e32 v36, v36
	v_exp_f32_e32 v37, v37
	s_nop 0
	v_pk_add_f32 v[36:37], v[36:37], 1.0 op_sel_hi:[1,0]
	s_nop 0
	v_div_scale_f32 v39, s[20:21], v37, v37, v38
	v_rcp_f32_e32 v40, v39
	s_nop 0
	v_fma_f32 v41, -v39, v40, 1.0
	v_fmac_f32_e32 v40, v41, v40
	v_div_scale_f32 v41, vcc, v38, v37, v38
	v_mul_f32_e32 v42, v41, v40
	v_fma_f32 v43, -v39, v42, v41
	v_fmac_f32_e32 v42, v43, v40
	v_fma_f32 v39, -v39, v42, v41
	v_div_fmas_f32 v39, v39, v40, v42
	v_div_fixup_f32 v37, v39, v37, v38
	v_div_scale_f32 v38, s[20:21], v36, v36, v4
	v_rcp_f32_e32 v39, v38
	s_nop 0
	v_fma_f32 v40, -v38, v39, 1.0
	v_fmac_f32_e32 v39, v40, v39
	v_div_scale_f32 v40, vcc, v4, v36, v4
	v_mul_f32_e32 v41, v40, v39
	v_fma_f32 v42, -v38, v41, v40
	v_fmac_f32_e32 v41, v42, v39
	v_fma_f32 v38, -v38, v41, v40
	v_div_fmas_f32 v38, v38, v39, v41
	v_div_fixup_f32 v36, v38, v36, v4
	v_and_b32_e32 v39, 0xffff0000, v84
	v_lshlrev_b32_e32 v38, 16, v84
	v_pk_mul_f32 v[36:37], v[36:37], v[38:39]
	v_and_b32_e32 v0, 0xffff0000, v89
	v_pk_mul_f32 v[32:33], v[32:33], v[36:37]
	v_lshlrev_b32_e32 v36, 16, v89
	v_mul_f32_e32 v4, 0xbfb8aa3b, v36
	v_mul_f32_e32 v5, 0xbfb8aa3b, v0
	v_exp_f32_e32 v4, v4
	v_exp_f32_e32 v5, v5
	s_nop 0
	v_pk_add_f32 v[4:5], v[4:5], 1.0 op_sel_hi:[1,0]
	s_nop 0
	v_div_scale_f32 v37, s[20:21], v5, v5, v0
	v_rcp_f32_e32 v38, v37
	s_nop 0
	v_fma_f32 v39, -v37, v38, 1.0
	v_fmac_f32_e32 v38, v39, v38
	v_div_scale_f32 v39, vcc, v0, v5, v0
	v_mul_f32_e32 v40, v39, v38
	v_fma_f32 v41, -v37, v40, v39
	v_fmac_f32_e32 v40, v41, v38
	v_fma_f32 v37, -v37, v40, v39
	v_div_fmas_f32 v37, v37, v38, v40
	v_div_fixup_f32 v5, v37, v5, v0
	v_div_scale_f32 v0, s[20:21], v4, v4, v36
	v_rcp_f32_e32 v37, v0
	s_nop 0
	v_fma_f32 v38, -v0, v37, 1.0
	v_fmac_f32_e32 v37, v38, v37
	v_div_scale_f32 v38, vcc, v36, v4, v36
	v_mul_f32_e32 v39, v38, v37
	v_fma_f32 v40, -v0, v39, v38
	v_fmac_f32_e32 v39, v40, v37
	v_fma_f32 v0, -v0, v39, v38
	v_div_fmas_f32 v0, v0, v37, v39
	v_div_fixup_f32 v4, v0, v4, v36
	v_and_b32_e32 v37, 0xffff0000, v85
	v_lshlrev_b32_e32 v36, 16, v85
	v_pk_mul_f32 v[0:1], v[4:5], v[36:37]
	v_add_f32_e32 v4, v67, v34
	v_add_f32_e32 v5, v67, v35
	v_and_b32_e32 v38, 0xffff0000, v90
	v_lshlrev_b32_e32 v6, 16, v90
	v_pk_mul_f32 v[0:1], v[4:5], v[0:1]
	v_mul_f32_e32 v4, 0xbfb8aa3b, v6
	v_mul_f32_e32 v5, 0xbfb8aa3b, v38
	v_exp_f32_e32 v4, v4
	v_exp_f32_e32 v5, v5
	ds_read_b128 v[34:37], v31 offset:4240
	v_pk_add_f32 v[4:5], v[4:5], 1.0 op_sel_hi:[1,0]
	s_nop 0
	v_div_scale_f32 v39, s[20:21], v5, v5, v38
	v_rcp_f32_e32 v40, v39
	s_waitcnt lgkmcnt(0)
	v_add_f32_e32 v34, v67, v34
	v_add_f32_e32 v35, v67, v35
	v_fma_f32 v41, -v39, v40, 1.0
	v_fmac_f32_e32 v40, v41, v40
	v_div_scale_f32 v41, vcc, v38, v5, v38
	v_mul_f32_e32 v42, v41, v40
	v_fma_f32 v43, -v39, v42, v41
	v_fmac_f32_e32 v42, v43, v40
	v_fma_f32 v39, -v39, v42, v41
	v_div_fmas_f32 v39, v39, v40, v42
	v_div_fixup_f32 v5, v39, v5, v38
	v_div_scale_f32 v38, s[20:21], v4, v4, v6
	v_rcp_f32_e32 v39, v38
	s_nop 0
	v_fma_f32 v40, -v38, v39, 1.0
	v_fmac_f32_e32 v39, v40, v39
	v_div_scale_f32 v40, vcc, v6, v4, v6
	v_mul_f32_e32 v41, v40, v39
	v_fma_f32 v42, -v38, v41, v40
	v_fmac_f32_e32 v41, v42, v39
	v_fma_f32 v38, -v38, v41, v40
	v_div_fmas_f32 v38, v38, v39, v41
	v_div_fixup_f32 v4, v38, v4, v6
	v_and_b32_e32 v39, 0xffff0000, v86
	v_lshlrev_b32_e32 v38, 16, v86
	v_pk_mul_f32 v[4:5], v[4:5], v[38:39]
	v_and_b32_e32 v2, 0xffff0000, v91
	v_pk_mul_f32 v[4:5], v[34:35], v[4:5]
	v_lshlrev_b32_e32 v34, 16, v91
	v_mul_f32_e32 v6, 0xbfb8aa3b, v34
	v_mul_f32_e32 v7, 0xbfb8aa3b, v2
	v_exp_f32_e32 v6, v6
	v_exp_f32_e32 v7, v7
	s_nop 0
	v_pk_add_f32 v[6:7], v[6:7], 1.0 op_sel_hi:[1,0]
	s_nop 0
	v_div_scale_f32 v35, s[20:21], v7, v7, v2
	v_rcp_f32_e32 v38, v35
	s_nop 0
	v_fma_f32 v39, -v35, v38, 1.0
	v_fmac_f32_e32 v38, v39, v38
	v_div_scale_f32 v39, vcc, v2, v7, v2
	v_mul_f32_e32 v40, v39, v38
	v_fma_f32 v41, -v35, v40, v39
	v_fmac_f32_e32 v40, v41, v38
	v_fma_f32 v35, -v35, v40, v39
	v_div_fmas_f32 v35, v35, v38, v40
	v_div_fixup_f32 v7, v35, v7, v2
	v_div_scale_f32 v2, s[20:21], v6, v6, v34
	v_rcp_f32_e32 v35, v2
	s_nop 0
	v_fma_f32 v38, -v2, v35, 1.0
	v_fmac_f32_e32 v35, v38, v35
	v_div_scale_f32 v38, vcc, v34, v6, v34
	v_mul_f32_e32 v39, v38, v35
	v_fma_f32 v40, -v2, v39, v38
	v_fmac_f32_e32 v39, v40, v35
	v_fma_f32 v2, -v2, v39, v38
	v_div_fmas_f32 v2, v2, v35, v39
	v_div_fixup_f32 v6, v2, v6, v34
	v_and_b32_e32 v35, 0xffff0000, v87
	v_lshlrev_b32_e32 v34, 16, v87
	v_pk_mul_f32 v[2:3], v[6:7], v[34:35]
	v_add_f32_e32 v6, v67, v36
	v_add_f32_e32 v7, v67, v37
	v_pk_mul_f32 v[2:3], v[6:7], v[2:3]
	v_cvt_pk_bf16_f32 v32, v32, v33
	v_cvt_pk_bf16_f32 v0, v0, v1
	v_cvt_pk_bf16_f32 v4, v4, v5
	v_cvt_pk_bf16_f32 v2, v2, v3
	v_mov_b32_e32 v3, v2
	v_mov_b32_e32 v2, v4
	v_mov_b32_e32 v1, v0
	v_mov_b32_e32 v0, v32
	v_lshl_add_u64 v[4:5], v[12:13], 0, v[160:161]
	global_store_dwordx4 v[4:5], v[0:3], off
	s_nop 0
	v_lshl_add_u64 v[12:13], v[12:13], 0, s[38:39]
	s_nop 0
	s_nop 0
	v_lshl_add_u64 v[10:11], v[10:11], 0, s[40:41]
	s_nop 0
	s_nop 0
	s_nop 0
	s_nop 0
	s_nop 0
	ds_read_b128 v[32:35], v31 offset:6336
	ds_read_b128 v[36:39], v31 offset:6352
	v_add_u32_e32 v31, 0x2100, v31
	s_waitcnt vmcnt(3)
	v_and_b32_e32 v29, 0xffff0000, v118
	v_lshlrev_b32_e32 v4, 16, v118
	v_mul_f32_e32 v30, 0xbfb8aa3b, v4
	v_exp_f32_e32 v40, v30
	v_mul_f32_e32 v30, 0xbfb8aa3b, v29
	v_exp_f32_e32 v41, v30
	s_nop 0
	v_pk_add_f32 v[40:41], v[40:41], 1.0 op_sel_hi:[1,0]
	s_nop 0
	v_div_scale_f32 v30, s[20:21], v41, v41, v29
	v_rcp_f32_e32 v42, v30
	s_nop 0
	v_fma_f32 v43, -v30, v42, 1.0
	v_fmac_f32_e32 v42, v43, v42
	v_div_scale_f32 v43, vcc, v29, v41, v29
	v_mul_f32_e32 v44, v43, v42
	v_fma_f32 v45, -v30, v44, v43
	v_fmac_f32_e32 v44, v45, v42
	v_fma_f32 v30, -v30, v44, v43
	v_div_fmas_f32 v30, v30, v42, v44
	v_div_fixup_f32 v41, v30, v41, v29
	v_div_scale_f32 v29, s[20:21], v40, v40, v4
	v_rcp_f32_e32 v30, v29
	s_nop 0
	v_fma_f32 v42, -v29, v30, 1.0
	v_fmac_f32_e32 v30, v42, v30
	v_div_scale_f32 v42, vcc, v4, v40, v4
	v_mul_f32_e32 v43, v42, v30
	v_fma_f32 v44, -v29, v43, v42
	v_fmac_f32_e32 v43, v44, v30
	v_fma_f32 v29, -v29, v43, v42
	v_div_fmas_f32 v29, v29, v30, v43
	v_div_fixup_f32 v40, v29, v40, v4
	v_and_b32_e32 v43, 0xffff0000, v114
	v_lshlrev_b32_e32 v42, 16, v114
	s_waitcnt lgkmcnt(1)
	v_add_f32_e32 v32, v92, v32
	v_add_f32_e32 v33, v92, v33
	v_and_b32_e32 v0, 0xffff0000, v119
	v_lshlrev_b32_e32 v29, 16, v119
	v_mul_f32_e32 v4, 0xbfb8aa3b, v29
	v_mul_f32_e32 v5, 0xbfb8aa3b, v0
	v_exp_f32_e32 v4, v4
	v_exp_f32_e32 v5, v5
	v_pk_mul_f32 v[40:41], v[40:41], v[42:43]
	v_pk_add_f32 v[4:5], v[4:5], 1.0 op_sel_hi:[1,0]
	s_nop 0
	v_div_scale_f32 v30, s[20:21], v5, v5, v0
	v_pk_mul_f32 v[32:33], v[32:33], v[40:41]
	v_rcp_f32_e32 v40, v30
	s_nop 0
	v_fma_f32 v41, -v30, v40, 1.0
	v_fmac_f32_e32 v40, v41, v40
	v_div_scale_f32 v41, vcc, v0, v5, v0
	v_mul_f32_e32 v42, v41, v40
	v_fma_f32 v43, -v30, v42, v41
	v_fmac_f32_e32 v42, v43, v40
	v_fma_f32 v30, -v30, v42, v41
	v_div_fmas_f32 v30, v30, v40, v42
	v_div_fixup_f32 v5, v30, v5, v0
	v_div_scale_f32 v0, s[20:21], v4, v4, v29
	v_rcp_f32_e32 v30, v0
	s_nop 0
	v_fma_f32 v40, -v0, v30, 1.0
	v_fmac_f32_e32 v30, v40, v30
	v_div_scale_f32 v40, vcc, v29, v4, v29
	v_mul_f32_e32 v41, v40, v30
	v_fma_f32 v42, -v0, v41, v40
	v_fmac_f32_e32 v41, v42, v30
	v_fma_f32 v0, -v0, v41, v40
	v_div_fmas_f32 v0, v0, v30, v41
	v_div_fixup_f32 v4, v0, v4, v29
	v_and_b32_e32 v41, 0xffff0000, v115
	v_lshlrev_b32_e32 v40, 16, v115
	v_pk_mul_f32 v[0:1], v[4:5], v[40:41]
	v_add_f32_e32 v4, v92, v34
	v_add_f32_e32 v5, v92, v35
	v_and_b32_e32 v29, 0xffff0000, v120
	v_lshlrev_b32_e32 v6, 16, v120
	v_pk_mul_f32 v[0:1], v[4:5], v[0:1]
	v_mul_f32_e32 v4, 0xbfb8aa3b, v6
	v_mul_f32_e32 v5, 0xbfb8aa3b, v29
	v_exp_f32_e32 v4, v4
	v_exp_f32_e32 v5, v5
	s_nop 0
	v_pk_add_f32 v[4:5], v[4:5], 1.0 op_sel_hi:[1,0]
	s_nop 0
	v_div_scale_f32 v30, s[20:21], v5, v5, v29
	v_rcp_f32_e32 v34, v30
	s_nop 0
	v_fma_f32 v35, -v30, v34, 1.0
	v_fmac_f32_e32 v34, v35, v34
	v_div_scale_f32 v35, vcc, v29, v5, v29
	v_mul_f32_e32 v40, v35, v34
	v_fma_f32 v41, -v30, v40, v35
	v_fmac_f32_e32 v40, v41, v34
	v_fma_f32 v30, -v30, v40, v35
	v_div_fmas_f32 v30, v30, v34, v40
	v_div_fixup_f32 v5, v30, v5, v29
	v_div_scale_f32 v29, s[20:21], v4, v4, v6
	v_rcp_f32_e32 v30, v29
	s_nop 0
	v_fma_f32 v34, -v29, v30, 1.0
	v_fmac_f32_e32 v30, v34, v30
	v_div_scale_f32 v34, vcc, v6, v4, v6
	v_mul_f32_e32 v35, v34, v30
	v_fma_f32 v40, -v29, v35, v34
	v_fmac_f32_e32 v35, v40, v30
	v_fma_f32 v29, -v29, v35, v34
	v_div_fmas_f32 v29, v29, v30, v35
	v_div_fixup_f32 v4, v29, v4, v6
	v_and_b32_e32 v35, 0xffff0000, v116
	v_lshlrev_b32_e32 v34, 16, v116
	v_pk_mul_f32 v[4:5], v[4:5], v[34:35]
	s_waitcnt lgkmcnt(0)
	v_add_f32_e32 v34, v92, v36
	v_add_f32_e32 v35, v92, v37
	v_and_b32_e32 v2, 0xffff0000, v121
	v_lshlrev_b32_e32 v29, 16, v121
	v_mul_f32_e32 v6, 0xbfb8aa3b, v29
	v_mul_f32_e32 v7, 0xbfb8aa3b, v2
	v_exp_f32_e32 v6, v6
	v_exp_f32_e32 v7, v7
	v_pk_mul_f32 v[4:5], v[34:35], v[4:5]
	v_pk_add_f32 v[6:7], v[6:7], 1.0 op_sel_hi:[1,0]
	s_nop 0
	v_div_scale_f32 v30, s[20:21], v7, v7, v2
	v_rcp_f32_e32 v34, v30
	s_nop 0
	v_fma_f32 v35, -v30, v34, 1.0
	v_fmac_f32_e32 v34, v35, v34
	v_div_scale_f32 v35, vcc, v2, v7, v2
	v_mul_f32_e32 v36, v35, v34
	v_fma_f32 v37, -v30, v36, v35
	v_fmac_f32_e32 v36, v37, v34
	v_fma_f32 v30, -v30, v36, v35
	v_div_fmas_f32 v30, v30, v34, v36
	v_div_fixup_f32 v7, v30, v7, v2
	v_div_scale_f32 v2, s[20:21], v6, v6, v29
	v_rcp_f32_e32 v30, v2
	s_nop 0
	v_fma_f32 v34, -v2, v30, 1.0
	v_fmac_f32_e32 v30, v34, v30
	v_div_scale_f32 v34, vcc, v29, v6, v29
	v_mul_f32_e32 v35, v34, v30
	v_fma_f32 v36, -v2, v35, v34
	v_fmac_f32_e32 v35, v36, v30
	v_fma_f32 v2, -v2, v35, v34
	v_div_fmas_f32 v2, v2, v30, v35
	v_div_fixup_f32 v6, v2, v6, v29
	v_and_b32_e32 v35, 0xffff0000, v117
	v_lshlrev_b32_e32 v34, 16, v117
	v_pk_mul_f32 v[2:3], v[6:7], v[34:35]
	v_add_f32_e32 v6, v92, v38
	v_add_f32_e32 v7, v92, v39
	v_pk_mul_f32 v[2:3], v[6:7], v[2:3]
	v_cvt_pk_bf16_f32 v32, v32, v33
	v_cvt_pk_bf16_f32 v0, v0, v1
	v_cvt_pk_bf16_f32 v4, v4, v5
	v_cvt_pk_bf16_f32 v2, v2, v3
	v_mov_b32_e32 v3, v2
	v_mov_b32_e32 v2, v4
	v_mov_b32_e32 v1, v0
	v_mov_b32_e32 v0, v32
	v_lshl_add_u64 v[4:5], v[8:9], 0, v[160:161]
	v_lshl_add_u64 v[8:9], v[8:9], 0, s[38:39]
	global_store_dwordx4 v[4:5], v[0:3], off
	v_mov_b32_e32 v28, v92
	s_cbranch_scc1 .LBB0_693
	s_barrier
